# in-proj A side job rows remapped onto units 0-3 of every workgroup (none in the last unit, in front of the phase-end barrier); on top of v82
# speedup vs baseline: 1.0034x; 1.0034x over previous
;     __device__ __forceinline__ void side_issue(Side& s, int ui, int c, int wid, int lane) const {
;         s.row = (c * upc + ui) * 8 + wid;
;     ...
;         typename Epi::Side side_; E.side_issue(side_, ui, S.c, wid, lane);
.LBB0_221:
	s_mul_i32 s2, s87, 5
	s_cmp_lg_u32 s2, s43
	s_cbranch_scc1 .Lsj_orig
	s_lshl_b32 s2, s87, 2
	s_add_i32 s2, s2, s27
	s_lshl_b32 s2, s2, 3
	s_add_i32 s76, s2, s14
	s_cmp_gt_u32 s27, 3
	s_cselect_b32 s76, 0x7fffffff, s76
	s_branch .Lsj_done

;     __device__ __forceinline__ void side_issue(Side& s, int ui, int c, int wid, int lane) const {
;         s.row = (c * upc + ui) * 8 + wid;
;         if (MODE == 0 && s.row < xrows) { const f32x4* xr = (const f32x4*)(xs + (size_t)s.row * 1024) + lane;
; #pragma unroll
;             for (int j = 0; j < 4; ++j) s.v[j] = __builtin_nontemporal_load(xr + 64 * j); }
.Lsj_done:
	s_cmp_lt_i32 s76, s95
	s_cselect_b64 s[80:81], -1, 0
	s_cmp_ge_i32 s76, s95
	s_cbranch_scc1 .LBB0_223
	s_ashr_i32 s77, s76, 31
	s_lshl_b64 s[38:39], s[76:77], 12
	v_lshl_add_u64 v[198:199], v[174:175], 0, s[38:39]
	global_load_dwordx4 v[210:213], v[198:199], off nt
	global_load_dwordx4 v[206:209], v[198:199], off offset:1024 nt
	global_load_dwordx4 v[202:205], v[198:199], off offset:2048 nt
	s_nop 0
	global_load_dwordx4 v[198:201], v[198:199], off offset:3072 nt
